# sparse attention: next key tile written to the other LDS buffer during the current block (one barrier per block, mid-step), K tile xor-swizzled for conflict-free b128 fragment reads, counted lgkm wait
# speedup vs baseline: 1.0184x; 1.0069x over previous
.LBB0_2063:
	s_or_b64 exec, exec, s[0:1]
	s_cmpk_gt_i32 s90, 0x3ff
	v_readlane_b32 s68, v251, 50
	v_readlane_b32 s69, v251, 51
	s_waitcnt lgkmcnt(0)
	s_barrier
	s_cbranch_scc1 .LBB0_2167
	v_readlane_b32 s0, v251, 7
	v_and_b32_e32 v112, 15, v152
	v_lshrrev_b32_e32 v113, 4, v152
	s_nop 1
	s_and_b32 s34, s0, 3
	s_lshr_b32 s35, s0, 2
	v_lshrrev_b32_e32 v220, 3, v153
	v_and_b32_e32 v221, 7, v153
	v_and_b32_e32 v222, 7, v220
	v_xor_b32_e32 v222, v222, v221
	v_lshlrev_b32_e32 v222, 4, v222
	v_lshl_add_u32 v114, v220, 7, v222
	v_mul_u32_u24_e32 v123, 0x90, v220
	v_lshl_add_u32 v123, v221, 4, v123
	v_add_u32_e32 v123, 0x2400, v123
	v_mul_u32_u24_e32 v117, 0x600, v220
	v_lshl_add_u32 v117, v221, 4, v117
	v_lshlrev_b32_e32 v118, 12, v220
	v_lshl_add_u32 v118, v221, 4, v118
	v_mul_u32_u24_e32 v116, 0x90, v112
	v_lshl_add_u32 v116, v113, 3, v116
	v_and_b32_e32 v222, 7, v112
	v_xor_b32_e32 v222, v222, v113
	v_lshlrev_b32_e32 v222, 4, v222
	v_lshl_add_u32 v115, v112, 7, v222
	v_xor_b32_e32 v122, 64, v115
	v_mov_b32_e32 v226, 0xf149f2ca
	v_mov_b32_e32 v227, 0x7f61b1e6
	v_mov_b32_e32 v238, 0
	v_mov_b32_e32 v224, 0xff800000
	s_mov_b32 s26, s90
	s_mov_b32 s50, 0

.Lnsa_brd_2:
	s_cmp_eq_u32 s37, 1
	s_mov_b32 s45, 0x7fffffff
	s_cselect_b32 s45, 0x200, s45
	s_add_i32 s14, s32, -8
	s_cmp_eq_u32 s37, 1
	s_cselect_b32 s14, s14, -2
	s_cselect_b64 vcc, -1, 0
	v_mov_b32_e32 v220, -1
	s_nop 1
	v_cndmask_b32_e32 v248, v84, v220, vcc
	v_cndmask_b32_e32 v249, v85, v220, vcc
	v_mov_b32_e32 v80, v226
	v_mov_b32_e32 v82, 0
	v_mov_b32_e32 v48, 0
	v_mov_b32_e32 v49, 0
	v_mov_b32_e32 v50, 0
	v_mov_b32_e32 v51, 0
	v_mov_b32_e32 v52, 0
	v_mov_b32_e32 v53, 0
	v_mov_b32_e32 v54, 0
	v_mov_b32_e32 v55, 0
	v_mov_b32_e32 v56, 0
	v_mov_b32_e32 v57, 0
	v_mov_b32_e32 v58, 0
	v_mov_b32_e32 v59, 0
	v_mov_b32_e32 v60, 0
	v_mov_b32_e32 v61, 0
	v_mov_b32_e32 v62, 0
	v_mov_b32_e32 v63, 0
	v_mov_b32_e32 v81, v226
	v_mov_b32_e32 v83, 0
	v_mov_b32_e32 v64, 0
	v_mov_b32_e32 v65, 0
	v_mov_b32_e32 v66, 0
	v_mov_b32_e32 v67, 0
	v_mov_b32_e32 v68, 0
	v_mov_b32_e32 v69, 0
	v_mov_b32_e32 v70, 0
	v_mov_b32_e32 v71, 0
	v_mov_b32_e32 v72, 0
	v_mov_b32_e32 v73, 0
	v_mov_b32_e32 v74, 0
	v_mov_b32_e32 v75, 0
	v_mov_b32_e32 v76, 0
	v_mov_b32_e32 v77, 0
	v_mov_b32_e32 v78, 0
	v_mov_b32_e32 v79, 0
	s_ff1_i32_b32 s15, s38
	s_add_i32 s65, s38, -1
	s_and_b32 s38, s38, s65
	s_ff1_i32_b32 s41, s38
	s_add_i32 s65, s38, -1
	s_and_b32 s38, s38, s65
	s_ff1_i32_b32 s42, s38
	s_add_i32 s65, s38, -1
	s_and_b32 s38, s38, s65
	s_cmp_eq_u32 s37, 1
	s_cbranch_scc0 .Lnsa_nopre_3
	v_mov_b32_e32 v88, v192
	v_mov_b32_e32 v92, v196
	v_mov_b32_e32 v89, v193
	v_mov_b32_e32 v93, v197
	v_mov_b32_e32 v90, v194
	v_mov_b32_e32 v94, v198
	v_mov_b32_e32 v91, v195
	v_mov_b32_e32 v95, v199
	s_branch .Lnsa_have0_4
.Lnsa_nopre_3:
	s_cmp_eq_u32 s15, 0
	s_cbranch_scc1 .Lnsa_have0_4
	s_mov_b32 s40, s15
	s_max_i32 s65, s40, 0
	s_mul_i32 s56, s65, 0x18000
	s_lshl_b32 s58, s65, 7
	s_add_u32 s56, s46, s56
	s_addc_u32 s57, s47, 0
	s_add_u32 s58, s48, s58
	s_addc_u32 s59, s49, 0
	global_load_dwordx4 v[88:91], v117, s[56:57]
	global_load_dwordx4 v[92:95], v118, s[58:59]
.Lnsa_have0_4:
	s_max_i32 s65, s41, 0
	s_mul_i32 s56, s65, 0x18000
	s_lshl_b32 s58, s65, 7
	s_add_u32 s56, s46, s56
	s_addc_u32 s57, s47, 0
	s_add_u32 s58, s48, s58
	s_addc_u32 s59, s49, 0
	global_load_dwordx4 v[96:99], v117, s[56:57]
	global_load_dwordx4 v[100:103], v118, s[58:59]
	s_max_i32 s65, s42, 0
	s_mul_i32 s56, s65, 0x18000
	s_lshl_b32 s58, s65, 7
	s_add_u32 s56, s46, s56
	s_addc_u32 s57, s47, 0
	s_add_u32 s58, s48, s58
	s_addc_u32 s59, s49, 0
	global_load_dwordx4 v[104:107], v117, s[56:57]
	global_load_dwordx4 v[108:111], v118, s[58:59]
	s_waitcnt vmcnt(4)
	v_add_u32_e32 v244, s50, v114
	v_add_u32_e32 v245, s50, v123
	ds_write_b128 v244, v[88:91]
	ds_write_b128 v245, v[92:95]
	s_ff1_i32_b32 s40, s38
	s_add_i32 s65, s38, -1
	s_and_b32 s38, s38, s65
	s_max_i32 s65, s40, 0
	s_mul_i32 s56, s65, 0x18000
	s_lshl_b32 s58, s65, 7
	s_add_u32 s56, s46, s56
	s_addc_u32 s57, s47, 0
	s_add_u32 s58, s48, s58
	s_addc_u32 s59, s49, 0
	global_load_dwordx4 v[88:91], v117, s[56:57]
	global_load_dwordx4 v[92:95], v118, s[58:59]
	s_waitcnt lgkmcnt(0)
	s_barrier
.Lnsa_loop_5:
	s_cmp_lt_i32 s15, 0
	s_cbranch_scc1 .Lnsa_brk_6
	v_add_u32_e32 v225, s50, v115
	v_add_u32_e32 v246, s50, v122
	ds_read_b128 v[160:163], v225 offset:0
	ds_read_b128 v[168:171], v225 offset:2048
	ds_read_b128 v[176:179], v225 offset:4096
	ds_read_b128 v[184:187], v225 offset:6144
	ds_read_b128 v[164:167], v246 offset:0
	ds_read_b128 v[172:175], v246 offset:2048
	ds_read_b128 v[180:183], v246 offset:4096
	ds_read_b128 v[188:191], v246 offset:6144
	v_add_u32_e32 v247, s50, v116
	s_lshl_b32 s44, s15, 6
	s_lshl_b32 s65, 1, s15
	v_and_b32_e32 v220, s65, v248
	v_and_b32_e32 v221, s65, v249
	v_lshl_add_u32 v222, v113, 2, s44
	v_cmp_ne_u32_e64 s[60:61], 0, v220
	v_cmp_ne_u32_e64 s[62:63], 0, v221
	v_sub_u32_e32 v120, v86, v222
	v_sub_u32_e32 v121, v87, v222
	s_cmp_eq_u32 s15, s32
	s_cselect_b32 s64, 1, 0
	s_cmp_eq_u32 s15, s14
	s_cselect_b32 s64, 1, s64
	s_xor_b32 s17, s50, 0x4800
	v_add_u32_e32 v244, s17, v114
	v_add_u32_e32 v245, s17, v123
	s_waitcnt lgkmcnt(7)
	v_mfma_f32_16x16x32_bf16 v[124:127], v[160:163], v[0:3], 0
	s_waitcnt lgkmcnt(6)
	v_mfma_f32_16x16x32_bf16 v[128:131], v[168:171], v[0:3], 0
	s_waitcnt lgkmcnt(5)
	v_mfma_f32_16x16x32_bf16 v[132:135], v[176:179], v[0:3], 0
	s_waitcnt lgkmcnt(4)
	v_mfma_f32_16x16x32_bf16 v[136:139], v[184:187], v[0:3], 0
	s_waitcnt lgkmcnt(3)
	v_mfma_f32_16x16x32_bf16 v[124:127], v[164:167], v[4:7], v[124:127]
	s_waitcnt lgkmcnt(2)
	v_mfma_f32_16x16x32_bf16 v[128:131], v[172:175], v[4:7], v[128:131]
	s_waitcnt lgkmcnt(1)
	v_mfma_f32_16x16x32_bf16 v[132:135], v[180:183], v[4:7], v[132:135]
	s_waitcnt lgkmcnt(0)
	v_mfma_f32_16x16x32_bf16 v[136:139], v[188:191], v[4:7], v[136:139]
	s_waitcnt vmcnt(4)
	ds_write_b128 v244, v[96:99]
	ds_write_b128 v245, v[100:103]
	s_mov_b32 s16, s41
	s_ff1_i32_b32 s41, s38
	s_add_i32 s65, s38, -1
	s_and_b32 s38, s38, s65
	s_max_i32 s65, s41, 0
	s_mul_i32 s56, s65, 0x18000
	s_lshl_b32 s58, s65, 7
	s_add_u32 s56, s46, s56
	s_addc_u32 s57, s47, 0
	s_add_u32 s58, s48, s58
	s_addc_u32 s59, s49, 0
	global_load_dwordx4 v[96:99], v117, s[56:57]
	global_load_dwordx4 v[100:103], v118, s[58:59]
	s_cmp_eq_u32 s64, 0
	s_cbranch_scc1 .Lnsa_nm_7
	v_cndmask_b32_e64 v240, -1, v120, s[60:61]
	v_subrev_u32_e32 v220, 0, v240
	v_subrev_u32_e32 v221, 1, v240
	v_subrev_u32_e32 v222, 2, v240
	v_subrev_u32_e32 v223, 3, v240
	v_cmp_gt_u32_e64 s[52:53], s45, v220
	v_cmp_gt_u32_e64 s[54:55], s45, v221
	v_cmp_gt_u32_e64 s[56:57], s45, v222
	v_cmp_gt_u32_e64 s[58:59], s45, v223
	v_cndmask_b32_e64 v124, v224, v124, s[52:53]
	v_cndmask_b32_e64 v125, v224, v125, s[54:55]
	v_cndmask_b32_e64 v126, v224, v126, s[56:57]
	v_cndmask_b32_e64 v127, v224, v127, s[58:59]
	v_subrev_u32_e32 v220, 16, v240
	v_subrev_u32_e32 v221, 17, v240
	v_subrev_u32_e32 v222, 18, v240
	v_subrev_u32_e32 v223, 19, v240
	v_cmp_gt_u32_e64 s[52:53], s45, v220
	v_cmp_gt_u32_e64 s[54:55], s45, v221
	v_cmp_gt_u32_e64 s[56:57], s45, v222
	v_cmp_gt_u32_e64 s[58:59], s45, v223
	v_cndmask_b32_e64 v128, v224, v128, s[52:53]
	v_cndmask_b32_e64 v129, v224, v129, s[54:55]
	v_cndmask_b32_e64 v130, v224, v130, s[56:57]
	v_cndmask_b32_e64 v131, v224, v131, s[58:59]
	v_subrev_u32_e32 v220, 32, v240
	v_subrev_u32_e32 v221, 33, v240
	v_subrev_u32_e32 v222, 34, v240
	v_subrev_u32_e32 v223, 35, v240
	v_cmp_gt_u32_e64 s[52:53], s45, v220
	v_cmp_gt_u32_e64 s[54:55], s45, v221
	v_cmp_gt_u32_e64 s[56:57], s45, v222
	v_cmp_gt_u32_e64 s[58:59], s45, v223
	v_cndmask_b32_e64 v132, v224, v132, s[52:53]
	v_cndmask_b32_e64 v133, v224, v133, s[54:55]
	v_cndmask_b32_e64 v134, v224, v134, s[56:57]
	v_cndmask_b32_e64 v135, v224, v135, s[58:59]
	v_subrev_u32_e32 v220, 48, v240
	v_subrev_u32_e32 v221, 49, v240
	v_subrev_u32_e32 v222, 50, v240
	v_subrev_u32_e32 v223, 51, v240
	v_cmp_gt_u32_e64 s[52:53], s45, v220
	v_cmp_gt_u32_e64 s[54:55], s45, v221
	v_cmp_gt_u32_e64 s[56:57], s45, v222
	v_cmp_gt_u32_e64 s[58:59], s45, v223
	v_cndmask_b32_e64 v136, v224, v136, s[52:53]
	v_cndmask_b32_e64 v137, v224, v137, s[54:55]
	v_cndmask_b32_e64 v138, v224, v138, s[56:57]
	v_cndmask_b32_e64 v139, v224, v139, s[58:59]

.Lnsa_nm_8:
	s_waitcnt lgkmcnt(0)
	s_barrier
	s_mov_b32 s50, s17
	s_mov_b32 s15, s16
	v_max3_f32 v220, v140, v141, v142
	v_max3_f32 v220, v220, v143, v144
	v_mfma_f32_16x16x32_bf16 v[48:51], v[160:163], v[204:207], v[48:51]
	v_max3_f32 v220, v220, v145, v146
	v_max3_f32 v220, v220, v147, v148
	v_max3_f32 v220, v220, v149, v150
	v_max3_f32 v220, v220, v151, v154
	v_max3_f32 v220, v220, v155, v156
	v_mfma_f32_16x16x32_bf16 v[52:55], v[168:171], v[204:207], v[52:55]
	v_max3_f32 v220, v220, v157, v226
	v_cndmask_b32_e64 v220, v226, v220, s[62:63]
	v_mov_b32_e32 v221, v220
	s_nop 1
	v_permlane16_swap_b32_e32 v220, v221
	v_mfma_f32_16x16x32_bf16 v[56:59], v[176:179], v[204:207], v[56:59]
	v_max_f32_e32 v220, v220, v221
	v_mov_b32_e32 v221, v220
	s_nop 1
	v_permlane32_swap_b32_e32 v220, v221
	v_max_f32_e32 v220, v220, v221
	v_mfma_f32_16x16x32_bf16 v[60:63], v[184:187], v[204:207], v[60:63]
	v_max_f32_e32 v222, v81, v220
	v_sub_f32_e32 v223, v81, v222
	v_exp_f32_e32 v230, v223
	v_mov_b32_e32 v81, v222
	v_cndmask_b32_e64 v222, v227, v222, s[62:63]
	v_mfma_f32_16x16x32_bf16 v[48:51], v[164:167], v[208:211], v[48:51]
	v_sub_f32_e32 v140, v140, v222
	v_sub_f32_e32 v141, v141, v222
	v_sub_f32_e32 v142, v142, v222
	v_sub_f32_e32 v143, v143, v222
	v_sub_f32_e32 v144, v144, v222
	v_mfma_f32_16x16x32_bf16 v[52:55], v[172:175], v[208:211], v[52:55]
	v_sub_f32_e32 v145, v145, v222
	v_sub_f32_e32 v146, v146, v222
	v_sub_f32_e32 v147, v147, v222
	v_sub_f32_e32 v148, v148, v222
	v_sub_f32_e32 v149, v149, v222
	v_mfma_f32_16x16x32_bf16 v[56:59], v[180:183], v[208:211], v[56:59]
	v_sub_f32_e32 v150, v150, v222
	v_sub_f32_e32 v151, v151, v222
	v_sub_f32_e32 v154, v154, v222
	v_sub_f32_e32 v155, v155, v222
	v_sub_f32_e32 v156, v156, v222
	v_mfma_f32_16x16x32_bf16 v[60:63], v[188:191], v[208:211], v[60:63]
	v_sub_f32_e32 v157, v157, v222
	v_exp_f32_e32 v140, v140
	v_exp_f32_e32 v141, v141
	v_exp_f32_e32 v142, v142
	v_exp_f32_e32 v143, v143
	v_exp_f32_e32 v144, v144
	v_exp_f32_e32 v145, v145
	v_exp_f32_e32 v146, v146
	v_exp_f32_e32 v147, v147
	v_exp_f32_e32 v148, v148
	v_exp_f32_e32 v149, v149
	v_exp_f32_e32 v150, v150
	v_exp_f32_e32 v151, v151
	v_exp_f32_e32 v154, v154
	v_exp_f32_e32 v155, v155
	v_exp_f32_e32 v156, v156
	v_exp_f32_e32 v157, v157
	v_mul_f32_e32 v83, v83, v230
	v_add_f32_e32 v232, 0, v140
	v_add_f32_e32 v232, v232, v141
	v_add_f32_e32 v232, v232, v142
	v_add_f32_e32 v232, v232, v143
	v_add_f32_e32 v232, v232, v144
	v_add_f32_e32 v232, v232, v145
	v_add_f32_e32 v232, v232, v146
	v_add_f32_e32 v232, v232, v147
	v_add_f32_e32 v232, v232, v148
	v_add_f32_e32 v232, v232, v149
	v_add_f32_e32 v232, v232, v150
	v_add_f32_e32 v232, v232, v151
	v_add_f32_e32 v232, v232, v154
	v_add_f32_e32 v232, v232, v155
	v_add_f32_e32 v232, v232, v156
	v_add_f32_e32 v232, v232, v157
	v_add_f32_e32 v83, v83, v232
	v_pk_mul_f32 v[64:65], v[64:65], v[230:231] op_sel_hi:[1,0]
	v_pk_mul_f32 v[66:67], v[66:67], v[230:231] op_sel_hi:[1,0]
	v_pk_mul_f32 v[68:69], v[68:69], v[230:231] op_sel_hi:[1,0]
	v_pk_mul_f32 v[70:71], v[70:71], v[230:231] op_sel_hi:[1,0]
	v_pk_mul_f32 v[72:73], v[72:73], v[230:231] op_sel_hi:[1,0]
	v_pk_mul_f32 v[74:75], v[74:75], v[230:231] op_sel_hi:[1,0]
	v_pk_mul_f32 v[76:77], v[76:77], v[230:231] op_sel_hi:[1,0]
	v_pk_mul_f32 v[78:79], v[78:79], v[230:231] op_sel_hi:[1,0]
	v_cvt_pk_bf16_f32 v212, v140, v141
	v_cvt_pk_bf16_f32 v213, v142, v143
	v_cvt_pk_bf16_f32 v214, v144, v145
	v_cvt_pk_bf16_f32 v215, v146, v147
	v_cvt_pk_bf16_f32 v216, v148, v149
	v_cvt_pk_bf16_f32 v217, v150, v151
	v_cvt_pk_bf16_f32 v218, v154, v155
	v_cvt_pk_bf16_f32 v219, v156, v157
	v_mfma_f32_16x16x32_bf16 v[64:67], v[160:163], v[212:215], v[64:67]
	v_mfma_f32_16x16x32_bf16 v[68:71], v[168:171], v[212:215], v[68:71]
	v_mfma_f32_16x16x32_bf16 v[72:75], v[176:179], v[212:215], v[72:75]
	v_mfma_f32_16x16x32_bf16 v[76:79], v[184:187], v[212:215], v[76:79]
	v_mfma_f32_16x16x32_bf16 v[64:67], v[164:167], v[216:219], v[64:67]
	v_mfma_f32_16x16x32_bf16 v[68:71], v[172:175], v[216:219], v[68:71]
	v_mfma_f32_16x16x32_bf16 v[72:75], v[180:183], v[216:219], v[72:75]
	v_mfma_f32_16x16x32_bf16 v[76:79], v[188:191], v[216:219], v[76:79]
	s_cmp_lt_i32 s15, 0
	s_cbranch_scc1 .Lnsa_brk_6
	v_add_u32_e32 v225, s50, v115
	v_add_u32_e32 v246, s50, v122
	ds_read_b128 v[160:163], v225 offset:0
	ds_read_b128 v[168:171], v225 offset:2048
	ds_read_b128 v[176:179], v225 offset:4096
	ds_read_b128 v[184:187], v225 offset:6144
	ds_read_b128 v[164:167], v246 offset:0
	ds_read_b128 v[172:175], v246 offset:2048
	ds_read_b128 v[180:183], v246 offset:4096
	ds_read_b128 v[188:191], v246 offset:6144
	v_add_u32_e32 v247, s50, v116
	s_lshl_b32 s44, s15, 6
	s_lshl_b32 s65, 1, s15
	v_and_b32_e32 v220, s65, v248
	v_and_b32_e32 v221, s65, v249
	v_lshl_add_u32 v222, v113, 2, s44
	v_cmp_ne_u32_e64 s[60:61], 0, v220
	v_cmp_ne_u32_e64 s[62:63], 0, v221
	v_sub_u32_e32 v120, v86, v222
	v_sub_u32_e32 v121, v87, v222
	s_cmp_eq_u32 s15, s32
	s_cselect_b32 s64, 1, 0
	s_cmp_eq_u32 s15, s14
	s_cselect_b32 s64, 1, s64
	s_xor_b32 s17, s50, 0x4800
	v_add_u32_e32 v244, s17, v114
	v_add_u32_e32 v245, s17, v123
	s_waitcnt lgkmcnt(7)
	v_mfma_f32_16x16x32_bf16 v[124:127], v[160:163], v[0:3], 0
	s_waitcnt lgkmcnt(6)
	v_mfma_f32_16x16x32_bf16 v[128:131], v[168:171], v[0:3], 0
	s_waitcnt lgkmcnt(5)
	v_mfma_f32_16x16x32_bf16 v[132:135], v[176:179], v[0:3], 0
	s_waitcnt lgkmcnt(4)
	v_mfma_f32_16x16x32_bf16 v[136:139], v[184:187], v[0:3], 0
	s_waitcnt lgkmcnt(3)
	v_mfma_f32_16x16x32_bf16 v[124:127], v[164:167], v[4:7], v[124:127]
	s_waitcnt lgkmcnt(2)
	v_mfma_f32_16x16x32_bf16 v[128:131], v[172:175], v[4:7], v[128:131]
	s_waitcnt lgkmcnt(1)
	v_mfma_f32_16x16x32_bf16 v[132:135], v[180:183], v[4:7], v[132:135]
	s_waitcnt lgkmcnt(0)
	v_mfma_f32_16x16x32_bf16 v[136:139], v[188:191], v[4:7], v[136:139]
	s_waitcnt vmcnt(4)
	ds_write_b128 v244, v[104:107]
	ds_write_b128 v245, v[108:111]
	s_mov_b32 s16, s42
	s_ff1_i32_b32 s42, s38
	s_add_i32 s65, s38, -1
	s_and_b32 s38, s38, s65
	s_max_i32 s65, s42, 0
	s_mul_i32 s56, s65, 0x18000
	s_lshl_b32 s58, s65, 7
	s_add_u32 s56, s46, s56
	s_addc_u32 s57, s47, 0
	s_add_u32 s58, s48, s58
	s_addc_u32 s59, s49, 0
	global_load_dwordx4 v[104:107], v117, s[56:57]
	global_load_dwordx4 v[108:111], v118, s[58:59]
	s_cmp_eq_u32 s64, 0
	s_cbranch_scc1 .Lnsa_nm_9
	v_cndmask_b32_e64 v240, -1, v120, s[60:61]
	v_subrev_u32_e32 v220, 0, v240
	v_subrev_u32_e32 v221, 1, v240
	v_subrev_u32_e32 v222, 2, v240
	v_subrev_u32_e32 v223, 3, v240
	v_cmp_gt_u32_e64 s[52:53], s45, v220
	v_cmp_gt_u32_e64 s[54:55], s45, v221
	v_cmp_gt_u32_e64 s[56:57], s45, v222
	v_cmp_gt_u32_e64 s[58:59], s45, v223
	v_cndmask_b32_e64 v124, v224, v124, s[52:53]
	v_cndmask_b32_e64 v125, v224, v125, s[54:55]
	v_cndmask_b32_e64 v126, v224, v126, s[56:57]
	v_cndmask_b32_e64 v127, v224, v127, s[58:59]
	v_subrev_u32_e32 v220, 16, v240
	v_subrev_u32_e32 v221, 17, v240
	v_subrev_u32_e32 v222, 18, v240
	v_subrev_u32_e32 v223, 19, v240
	v_cmp_gt_u32_e64 s[52:53], s45, v220
	v_cmp_gt_u32_e64 s[54:55], s45, v221
	v_cmp_gt_u32_e64 s[56:57], s45, v222
	v_cmp_gt_u32_e64 s[58:59], s45, v223
	v_cndmask_b32_e64 v128, v224, v128, s[52:53]
	v_cndmask_b32_e64 v129, v224, v129, s[54:55]
	v_cndmask_b32_e64 v130, v224, v130, s[56:57]
	v_cndmask_b32_e64 v131, v224, v131, s[58:59]
	v_subrev_u32_e32 v220, 32, v240
	v_subrev_u32_e32 v221, 33, v240
	v_subrev_u32_e32 v222, 34, v240
	v_subrev_u32_e32 v223, 35, v240
	v_cmp_gt_u32_e64 s[52:53], s45, v220
	v_cmp_gt_u32_e64 s[54:55], s45, v221
	v_cmp_gt_u32_e64 s[56:57], s45, v222
	v_cmp_gt_u32_e64 s[58:59], s45, v223
	v_cndmask_b32_e64 v132, v224, v132, s[52:53]
	v_cndmask_b32_e64 v133, v224, v133, s[54:55]
	v_cndmask_b32_e64 v134, v224, v134, s[56:57]
	v_cndmask_b32_e64 v135, v224, v135, s[58:59]
	v_subrev_u32_e32 v220, 48, v240
	v_subrev_u32_e32 v221, 49, v240
	v_subrev_u32_e32 v222, 50, v240
	v_subrev_u32_e32 v223, 51, v240
	v_cmp_gt_u32_e64 s[52:53], s45, v220
	v_cmp_gt_u32_e64 s[54:55], s45, v221
	v_cmp_gt_u32_e64 s[56:57], s45, v222
	v_cmp_gt_u32_e64 s[58:59], s45, v223
	v_cndmask_b32_e64 v136, v224, v136, s[52:53]
	v_cndmask_b32_e64 v137, v224, v137, s[54:55]
	v_cndmask_b32_e64 v138, v224, v138, s[56:57]
	v_cndmask_b32_e64 v139, v224, v139, s[58:59]

.Lnsa_nm_10:
	s_waitcnt lgkmcnt(0)
	s_barrier
	s_mov_b32 s50, s17
	s_mov_b32 s15, s16
	v_max3_f32 v220, v140, v141, v142
	v_max3_f32 v220, v220, v143, v144
	v_mfma_f32_16x16x32_bf16 v[48:51], v[160:163], v[204:207], v[48:51]
	v_max3_f32 v220, v220, v145, v146
	v_max3_f32 v220, v220, v147, v148
	v_max3_f32 v220, v220, v149, v150
	v_max3_f32 v220, v220, v151, v154
	v_max3_f32 v220, v220, v155, v156
	v_mfma_f32_16x16x32_bf16 v[52:55], v[168:171], v[204:207], v[52:55]
	v_max3_f32 v220, v220, v157, v226
	v_cndmask_b32_e64 v220, v226, v220, s[62:63]
	v_mov_b32_e32 v221, v220
	s_nop 1
	v_permlane16_swap_b32_e32 v220, v221
	v_mfma_f32_16x16x32_bf16 v[56:59], v[176:179], v[204:207], v[56:59]
	v_max_f32_e32 v220, v220, v221
	v_mov_b32_e32 v221, v220
	s_nop 1
	v_permlane32_swap_b32_e32 v220, v221
	v_max_f32_e32 v220, v220, v221
	v_mfma_f32_16x16x32_bf16 v[60:63], v[184:187], v[204:207], v[60:63]
	v_max_f32_e32 v222, v81, v220
	v_sub_f32_e32 v223, v81, v222
	v_exp_f32_e32 v230, v223
	v_mov_b32_e32 v81, v222
	v_cndmask_b32_e64 v222, v227, v222, s[62:63]
	v_mfma_f32_16x16x32_bf16 v[48:51], v[164:167], v[208:211], v[48:51]
	v_sub_f32_e32 v140, v140, v222
	v_sub_f32_e32 v141, v141, v222
	v_sub_f32_e32 v142, v142, v222
	v_sub_f32_e32 v143, v143, v222
	v_sub_f32_e32 v144, v144, v222
	v_mfma_f32_16x16x32_bf16 v[52:55], v[172:175], v[208:211], v[52:55]
	v_sub_f32_e32 v145, v145, v222
	v_sub_f32_e32 v146, v146, v222
	v_sub_f32_e32 v147, v147, v222
	v_sub_f32_e32 v148, v148, v222
	v_sub_f32_e32 v149, v149, v222
	v_mfma_f32_16x16x32_bf16 v[56:59], v[180:183], v[208:211], v[56:59]
	v_sub_f32_e32 v150, v150, v222
	v_sub_f32_e32 v151, v151, v222
	v_sub_f32_e32 v154, v154, v222
	v_sub_f32_e32 v155, v155, v222
	v_sub_f32_e32 v156, v156, v222
	v_mfma_f32_16x16x32_bf16 v[60:63], v[188:191], v[208:211], v[60:63]
	v_sub_f32_e32 v157, v157, v222
	v_exp_f32_e32 v140, v140
	v_exp_f32_e32 v141, v141
	v_exp_f32_e32 v142, v142
	v_exp_f32_e32 v143, v143
	v_exp_f32_e32 v144, v144
	v_exp_f32_e32 v145, v145
	v_exp_f32_e32 v146, v146
	v_exp_f32_e32 v147, v147
	v_exp_f32_e32 v148, v148
	v_exp_f32_e32 v149, v149
	v_exp_f32_e32 v150, v150
	v_exp_f32_e32 v151, v151
	v_exp_f32_e32 v154, v154
	v_exp_f32_e32 v155, v155
	v_exp_f32_e32 v156, v156
	v_exp_f32_e32 v157, v157
	v_mul_f32_e32 v83, v83, v230
	v_add_f32_e32 v232, 0, v140
	v_add_f32_e32 v232, v232, v141
	v_add_f32_e32 v232, v232, v142
	v_add_f32_e32 v232, v232, v143
	v_add_f32_e32 v232, v232, v144
	v_add_f32_e32 v232, v232, v145
	v_add_f32_e32 v232, v232, v146
	v_add_f32_e32 v232, v232, v147
	v_add_f32_e32 v232, v232, v148
	v_add_f32_e32 v232, v232, v149
	v_add_f32_e32 v232, v232, v150
	v_add_f32_e32 v232, v232, v151
	v_add_f32_e32 v232, v232, v154
	v_add_f32_e32 v232, v232, v155
	v_add_f32_e32 v232, v232, v156
	v_add_f32_e32 v232, v232, v157
	v_add_f32_e32 v83, v83, v232
	v_pk_mul_f32 v[64:65], v[64:65], v[230:231] op_sel_hi:[1,0]
	v_pk_mul_f32 v[66:67], v[66:67], v[230:231] op_sel_hi:[1,0]
	v_pk_mul_f32 v[68:69], v[68:69], v[230:231] op_sel_hi:[1,0]
	v_pk_mul_f32 v[70:71], v[70:71], v[230:231] op_sel_hi:[1,0]
	v_pk_mul_f32 v[72:73], v[72:73], v[230:231] op_sel_hi:[1,0]
	v_pk_mul_f32 v[74:75], v[74:75], v[230:231] op_sel_hi:[1,0]
	v_pk_mul_f32 v[76:77], v[76:77], v[230:231] op_sel_hi:[1,0]
	v_pk_mul_f32 v[78:79], v[78:79], v[230:231] op_sel_hi:[1,0]
	v_cvt_pk_bf16_f32 v212, v140, v141
	v_cvt_pk_bf16_f32 v213, v142, v143
	v_cvt_pk_bf16_f32 v214, v144, v145
	v_cvt_pk_bf16_f32 v215, v146, v147
	v_cvt_pk_bf16_f32 v216, v148, v149
	v_cvt_pk_bf16_f32 v217, v150, v151
	v_cvt_pk_bf16_f32 v218, v154, v155
	v_cvt_pk_bf16_f32 v219, v156, v157
	v_mfma_f32_16x16x32_bf16 v[64:67], v[160:163], v[212:215], v[64:67]
	v_mfma_f32_16x16x32_bf16 v[68:71], v[168:171], v[212:215], v[68:71]
	v_mfma_f32_16x16x32_bf16 v[72:75], v[176:179], v[212:215], v[72:75]
	v_mfma_f32_16x16x32_bf16 v[76:79], v[184:187], v[212:215], v[76:79]
	v_mfma_f32_16x16x32_bf16 v[64:67], v[164:167], v[216:219], v[64:67]
	v_mfma_f32_16x16x32_bf16 v[68:71], v[172:175], v[216:219], v[68:71]
	v_mfma_f32_16x16x32_bf16 v[72:75], v[180:183], v[216:219], v[72:75]
	v_mfma_f32_16x16x32_bf16 v[76:79], v[188:191], v[216:219], v[76:79]
	s_cmp_lt_i32 s15, 0
	s_cbranch_scc1 .Lnsa_brk_6
	v_add_u32_e32 v225, s50, v115
	v_add_u32_e32 v246, s50, v122
	ds_read_b128 v[160:163], v225 offset:0
	ds_read_b128 v[168:171], v225 offset:2048
	ds_read_b128 v[176:179], v225 offset:4096
	ds_read_b128 v[184:187], v225 offset:6144
	ds_read_b128 v[164:167], v246 offset:0
	ds_read_b128 v[172:175], v246 offset:2048
	ds_read_b128 v[180:183], v246 offset:4096
	ds_read_b128 v[188:191], v246 offset:6144
	v_add_u32_e32 v247, s50, v116
	s_lshl_b32 s44, s15, 6
	s_lshl_b32 s65, 1, s15
	v_and_b32_e32 v220, s65, v248
	v_and_b32_e32 v221, s65, v249
	v_lshl_add_u32 v222, v113, 2, s44
	v_cmp_ne_u32_e64 s[60:61], 0, v220
	v_cmp_ne_u32_e64 s[62:63], 0, v221
	v_sub_u32_e32 v120, v86, v222
	v_sub_u32_e32 v121, v87, v222
	s_cmp_eq_u32 s15, s32
	s_cselect_b32 s64, 1, 0
	s_cmp_eq_u32 s15, s14
	s_cselect_b32 s64, 1, s64
	s_xor_b32 s17, s50, 0x4800
	v_add_u32_e32 v244, s17, v114
	v_add_u32_e32 v245, s17, v123
	s_waitcnt lgkmcnt(7)
	v_mfma_f32_16x16x32_bf16 v[124:127], v[160:163], v[0:3], 0
	s_waitcnt lgkmcnt(6)
	v_mfma_f32_16x16x32_bf16 v[128:131], v[168:171], v[0:3], 0
	s_waitcnt lgkmcnt(5)
	v_mfma_f32_16x16x32_bf16 v[132:135], v[176:179], v[0:3], 0
	s_waitcnt lgkmcnt(4)
	v_mfma_f32_16x16x32_bf16 v[136:139], v[184:187], v[0:3], 0
	s_waitcnt lgkmcnt(3)
	v_mfma_f32_16x16x32_bf16 v[124:127], v[164:167], v[4:7], v[124:127]
	s_waitcnt lgkmcnt(2)
	v_mfma_f32_16x16x32_bf16 v[128:131], v[172:175], v[4:7], v[128:131]
	s_waitcnt lgkmcnt(1)
	v_mfma_f32_16x16x32_bf16 v[132:135], v[180:183], v[4:7], v[132:135]
	s_waitcnt lgkmcnt(0)
	v_mfma_f32_16x16x32_bf16 v[136:139], v[188:191], v[4:7], v[136:139]
	s_waitcnt vmcnt(4)
	ds_write_b128 v244, v[88:91]
	ds_write_b128 v245, v[92:95]
	s_mov_b32 s16, s40
	s_ff1_i32_b32 s40, s38
	s_add_i32 s65, s38, -1
	s_and_b32 s38, s38, s65
	s_max_i32 s65, s40, 0
	s_mul_i32 s56, s65, 0x18000
	s_lshl_b32 s58, s65, 7
	s_add_u32 s56, s46, s56
	s_addc_u32 s57, s47, 0
	s_add_u32 s58, s48, s58
	s_addc_u32 s59, s49, 0
	global_load_dwordx4 v[88:91], v117, s[56:57]
	global_load_dwordx4 v[92:95], v118, s[58:59]
	s_cmp_eq_u32 s64, 0
	s_cbranch_scc1 .Lnsa_nm_11
	v_cndmask_b32_e64 v240, -1, v120, s[60:61]
	v_subrev_u32_e32 v220, 0, v240
	v_subrev_u32_e32 v221, 1, v240
	v_subrev_u32_e32 v222, 2, v240
	v_subrev_u32_e32 v223, 3, v240
	v_cmp_gt_u32_e64 s[52:53], s45, v220
	v_cmp_gt_u32_e64 s[54:55], s45, v221
	v_cmp_gt_u32_e64 s[56:57], s45, v222
	v_cmp_gt_u32_e64 s[58:59], s45, v223
	v_cndmask_b32_e64 v124, v224, v124, s[52:53]
	v_cndmask_b32_e64 v125, v224, v125, s[54:55]
	v_cndmask_b32_e64 v126, v224, v126, s[56:57]
	v_cndmask_b32_e64 v127, v224, v127, s[58:59]
	v_subrev_u32_e32 v220, 16, v240
	v_subrev_u32_e32 v221, 17, v240
	v_subrev_u32_e32 v222, 18, v240
	v_subrev_u32_e32 v223, 19, v240
	v_cmp_gt_u32_e64 s[52:53], s45, v220
	v_cmp_gt_u32_e64 s[54:55], s45, v221
	v_cmp_gt_u32_e64 s[56:57], s45, v222
	v_cmp_gt_u32_e64 s[58:59], s45, v223
	v_cndmask_b32_e64 v128, v224, v128, s[52:53]
	v_cndmask_b32_e64 v129, v224, v129, s[54:55]
	v_cndmask_b32_e64 v130, v224, v130, s[56:57]
	v_cndmask_b32_e64 v131, v224, v131, s[58:59]
	v_subrev_u32_e32 v220, 32, v240
	v_subrev_u32_e32 v221, 33, v240
	v_subrev_u32_e32 v222, 34, v240
	v_subrev_u32_e32 v223, 35, v240
	v_cmp_gt_u32_e64 s[52:53], s45, v220
	v_cmp_gt_u32_e64 s[54:55], s45, v221
	v_cmp_gt_u32_e64 s[56:57], s45, v222
	v_cmp_gt_u32_e64 s[58:59], s45, v223
	v_cndmask_b32_e64 v132, v224, v132, s[52:53]
	v_cndmask_b32_e64 v133, v224, v133, s[54:55]
	v_cndmask_b32_e64 v134, v224, v134, s[56:57]
	v_cndmask_b32_e64 v135, v224, v135, s[58:59]
	v_subrev_u32_e32 v220, 48, v240
	v_subrev_u32_e32 v221, 49, v240
	v_subrev_u32_e32 v222, 50, v240
	v_subrev_u32_e32 v223, 51, v240
	v_cmp_gt_u32_e64 s[52:53], s45, v220
	v_cmp_gt_u32_e64 s[54:55], s45, v221
	v_cmp_gt_u32_e64 s[56:57], s45, v222
	v_cmp_gt_u32_e64 s[58:59], s45, v223
	v_cndmask_b32_e64 v136, v224, v136, s[52:53]
	v_cndmask_b32_e64 v137, v224, v137, s[54:55]
	v_cndmask_b32_e64 v138, v224, v138, s[56:57]
	v_cndmask_b32_e64 v139, v224, v139, s[58:59]

.Lnsa_nm_12:
	s_waitcnt lgkmcnt(0)
	s_barrier
	s_mov_b32 s50, s17
	s_mov_b32 s15, s16
	v_max3_f32 v220, v140, v141, v142
	v_max3_f32 v220, v220, v143, v144
	v_mfma_f32_16x16x32_bf16 v[48:51], v[160:163], v[204:207], v[48:51]
	v_max3_f32 v220, v220, v145, v146
	v_max3_f32 v220, v220, v147, v148
	v_max3_f32 v220, v220, v149, v150
	v_max3_f32 v220, v220, v151, v154
	v_max3_f32 v220, v220, v155, v156
	v_mfma_f32_16x16x32_bf16 v[52:55], v[168:171], v[204:207], v[52:55]
	v_max3_f32 v220, v220, v157, v226
	v_cndmask_b32_e64 v220, v226, v220, s[62:63]
	v_mov_b32_e32 v221, v220
	s_nop 1
	v_permlane16_swap_b32_e32 v220, v221
	v_mfma_f32_16x16x32_bf16 v[56:59], v[176:179], v[204:207], v[56:59]
	v_max_f32_e32 v220, v220, v221
	v_mov_b32_e32 v221, v220
	s_nop 1
	v_permlane32_swap_b32_e32 v220, v221
	v_max_f32_e32 v220, v220, v221
	v_mfma_f32_16x16x32_bf16 v[60:63], v[184:187], v[204:207], v[60:63]
	v_max_f32_e32 v222, v81, v220
	v_sub_f32_e32 v223, v81, v222
	v_exp_f32_e32 v230, v223
	v_mov_b32_e32 v81, v222
	v_cndmask_b32_e64 v222, v227, v222, s[62:63]
	v_mfma_f32_16x16x32_bf16 v[48:51], v[164:167], v[208:211], v[48:51]
	v_sub_f32_e32 v140, v140, v222
	v_sub_f32_e32 v141, v141, v222
	v_sub_f32_e32 v142, v142, v222
	v_sub_f32_e32 v143, v143, v222
	v_sub_f32_e32 v144, v144, v222
	v_mfma_f32_16x16x32_bf16 v[52:55], v[172:175], v[208:211], v[52:55]
	v_sub_f32_e32 v145, v145, v222
	v_sub_f32_e32 v146, v146, v222
	v_sub_f32_e32 v147, v147, v222
	v_sub_f32_e32 v148, v148, v222
	v_sub_f32_e32 v149, v149, v222
	v_mfma_f32_16x16x32_bf16 v[56:59], v[180:183], v[208:211], v[56:59]
	v_sub_f32_e32 v150, v150, v222
	v_sub_f32_e32 v151, v151, v222
	v_sub_f32_e32 v154, v154, v222
	v_sub_f32_e32 v155, v155, v222
	v_sub_f32_e32 v156, v156, v222
	v_mfma_f32_16x16x32_bf16 v[60:63], v[188:191], v[208:211], v[60:63]
	v_sub_f32_e32 v157, v157, v222
	v_exp_f32_e32 v140, v140
	v_exp_f32_e32 v141, v141
	v_exp_f32_e32 v142, v142
	v_exp_f32_e32 v143, v143
	v_exp_f32_e32 v144, v144
	v_exp_f32_e32 v145, v145
	v_exp_f32_e32 v146, v146
	v_exp_f32_e32 v147, v147
	v_exp_f32_e32 v148, v148
	v_exp_f32_e32 v149, v149
	v_exp_f32_e32 v150, v150
	v_exp_f32_e32 v151, v151
	v_exp_f32_e32 v154, v154
	v_exp_f32_e32 v155, v155
	v_exp_f32_e32 v156, v156
	v_exp_f32_e32 v157, v157
	v_mul_f32_e32 v83, v83, v230
	v_add_f32_e32 v232, 0, v140
	v_add_f32_e32 v232, v232, v141
	v_add_f32_e32 v232, v232, v142
	v_add_f32_e32 v232, v232, v143
	v_add_f32_e32 v232, v232, v144
	v_add_f32_e32 v232, v232, v145
	v_add_f32_e32 v232, v232, v146
	v_add_f32_e32 v232, v232, v147
	v_add_f32_e32 v232, v232, v148
	v_add_f32_e32 v232, v232, v149
	v_add_f32_e32 v232, v232, v150
	v_add_f32_e32 v232, v232, v151
	v_add_f32_e32 v232, v232, v154
	v_add_f32_e32 v232, v232, v155
	v_add_f32_e32 v232, v232, v156
	v_add_f32_e32 v232, v232, v157
	v_add_f32_e32 v83, v83, v232
	v_pk_mul_f32 v[64:65], v[64:65], v[230:231] op_sel_hi:[1,0]
	v_pk_mul_f32 v[66:67], v[66:67], v[230:231] op_sel_hi:[1,0]
	v_pk_mul_f32 v[68:69], v[68:69], v[230:231] op_sel_hi:[1,0]
	v_pk_mul_f32 v[70:71], v[70:71], v[230:231] op_sel_hi:[1,0]
	v_pk_mul_f32 v[72:73], v[72:73], v[230:231] op_sel_hi:[1,0]
	v_pk_mul_f32 v[74:75], v[74:75], v[230:231] op_sel_hi:[1,0]
	v_pk_mul_f32 v[76:77], v[76:77], v[230:231] op_sel_hi:[1,0]
	v_pk_mul_f32 v[78:79], v[78:79], v[230:231] op_sel_hi:[1,0]
	v_cvt_pk_bf16_f32 v212, v140, v141
	v_cvt_pk_bf16_f32 v213, v142, v143
	v_cvt_pk_bf16_f32 v214, v144, v145
	v_cvt_pk_bf16_f32 v215, v146, v147
	v_cvt_pk_bf16_f32 v216, v148, v149
	v_cvt_pk_bf16_f32 v217, v150, v151
	v_cvt_pk_bf16_f32 v218, v154, v155
	v_cvt_pk_bf16_f32 v219, v156, v157
	v_mfma_f32_16x16x32_bf16 v[64:67], v[160:163], v[212:215], v[64:67]
	v_mfma_f32_16x16x32_bf16 v[68:71], v[168:171], v[212:215], v[68:71]
	v_mfma_f32_16x16x32_bf16 v[72:75], v[176:179], v[212:215], v[72:75]
	v_mfma_f32_16x16x32_bf16 v[76:79], v[184:187], v[212:215], v[76:79]
	v_mfma_f32_16x16x32_bf16 v[64:67], v[164:167], v[216:219], v[64:67]
	v_mfma_f32_16x16x32_bf16 v[68:71], v[172:175], v[216:219], v[68:71]
	v_mfma_f32_16x16x32_bf16 v[72:75], v[180:183], v[216:219], v[72:75]
	v_mfma_f32_16x16x32_bf16 v[76:79], v[188:191], v[216:219], v[76:79]
	s_branch .Lnsa_loop_5
.Lnsa_brk_6:
	s_waitcnt vmcnt(0)
	s_nop 7
	s_lshl_b32 s3, s30, 11
	v_mov_b32_e32 v221, v82
	s_nop 1
	v_permlane16_swap_b32_e32 v82, v221
	v_add_f32_e32 v82, v82, v221
	v_mov_b32_e32 v221, v82
	s_nop 1
	v_permlane32_swap_b32_e32 v82, v221
	v_add_f32_e32 v82, v82, v221
	v_max_f32_e32 v220, 0xda24260, v82
	s_cmp_eq_u32 s37, 1
	s_cselect_b64 vcc, -1, 0
	s_nop 1
	v_cndmask_b32_e32 v222, v119, v158, vcc
	v_lshlrev_b32_e32 v222, 16, v222
	v_div_scale_f32 v240, s[52:53], v220, v220, v222
	v_rcp_f32_e32 v241, v240
	v_div_scale_f32 v242, vcc, v222, v220, v222
	v_fma_f32 v243, -v240, v241, 1.0
	v_fmac_f32_e32 v241, v243, v241
	v_mul_f32_e32 v243, v242, v241
	v_fma_f32 v244, -v240, v243, v242
	v_fmac_f32_e32 v243, v244, v241
	v_fma_f32 v240, -v240, v243, v242
	s_nop 1
	v_div_fmas_f32 v240, v240, v241, v243
	v_div_fixup_f32 v228, v240, v220, v222
	v_pk_fma_f32 v[16:17], v[48:49], v[228:229], v[16:17] op_sel_hi:[1,0,1]
	v_pk_fma_f32 v[18:19], v[50:51], v[228:229], v[18:19] op_sel_hi:[1,0,1]
	v_pk_fma_f32 v[20:21], v[52:53], v[228:229], v[20:21] op_sel_hi:[1,0,1]
	v_pk_fma_f32 v[22:23], v[54:55], v[228:229], v[22:23] op_sel_hi:[1,0,1]
	v_pk_fma_f32 v[24:25], v[56:57], v[228:229], v[24:25] op_sel_hi:[1,0,1]
	v_pk_fma_f32 v[26:27], v[58:59], v[228:229], v[26:27] op_sel_hi:[1,0,1]
	v_pk_fma_f32 v[28:29], v[60:61], v[228:229], v[28:29] op_sel_hi:[1,0,1]
	v_pk_fma_f32 v[30:31], v[62:63], v[228:229], v[30:31] op_sel_hi:[1,0,1]
	v_mov_b32_e32 v221, v83
	s_nop 1
	v_permlane16_swap_b32_e32 v83, v221
	v_add_f32_e32 v83, v83, v221
	v_mov_b32_e32 v221, v83
	s_nop 1
	v_permlane32_swap_b32_e32 v83, v221
	v_add_f32_e32 v83, v83, v221
	v_max_f32_e32 v220, 0xda24260, v83
	s_cmp_eq_u32 s37, 1
	s_cselect_b64 vcc, -1, 0
	s_nop 1
	v_cndmask_b32_e32 v222, v159, v233, vcc
	v_lshlrev_b32_e32 v222, 16, v222
	v_div_scale_f32 v240, s[52:53], v220, v220, v222
	v_rcp_f32_e32 v241, v240
	v_div_scale_f32 v242, vcc, v222, v220, v222
	v_fma_f32 v243, -v240, v241, 1.0
	v_fmac_f32_e32 v241, v243, v241
	v_mul_f32_e32 v243, v242, v241
	v_fma_f32 v244, -v240, v243, v242
	v_fmac_f32_e32 v243, v244, v241
	v_fma_f32 v240, -v240, v243, v242
	s_nop 1
	v_div_fmas_f32 v240, v240, v241, v243
	v_div_fixup_f32 v228, v240, v220, v222
	v_pk_fma_f32 v[32:33], v[64:65], v[228:229], v[32:33] op_sel_hi:[1,0,1]
	v_pk_fma_f32 v[34:35], v[66:67], v[228:229], v[34:35] op_sel_hi:[1,0,1]
	v_pk_fma_f32 v[36:37], v[68:69], v[228:229], v[36:37] op_sel_hi:[1,0,1]
	v_pk_fma_f32 v[38:39], v[70:71], v[228:229], v[38:39] op_sel_hi:[1,0,1]
	v_pk_fma_f32 v[40:41], v[72:73], v[228:229], v[40:41] op_sel_hi:[1,0,1]
	v_pk_fma_f32 v[42:43], v[74:75], v[228:229], v[42:43] op_sel_hi:[1,0,1]
	v_pk_fma_f32 v[44:45], v[76:77], v[228:229], v[44:45] op_sel_hi:[1,0,1]
	v_pk_fma_f32 v[46:47], v[78:79], v[228:229], v[46:47] op_sel_hi:[1,0,1]
	s_add_i32 s37, s37, 1
	s_cmp_lt_u32 s37, 2
	s_cbranch_scc1 .Lnsa_br
	s_lshl_b32 s3, s30, 11
	s_add_u32 s8, s96, 0x9000000
	s_addc_u32 s9, s97, 0
	v_add_u32_e32 v223, s3, v86
	v_lshlrev_b32_e32 v223, 10, v223
	s_lshl_b32 s2, s36, 7
	v_add_u32_e32 v223, s2, v223
	v_lshl_add_u32 v223, v113, 3, v223
	v_cvt_pk_bf16_f32 v240, v16, v17
	v_cvt_pk_bf16_f32 v241, v18, v19
	global_store_dwordx2 v223, v[240:241], s[8:9] offset:0
	v_cvt_pk_bf16_f32 v240, v20, v21
	v_cvt_pk_bf16_f32 v241, v22, v23
	global_store_dwordx2 v223, v[240:241], s[8:9] offset:32
	v_cvt_pk_bf16_f32 v240, v24, v25
	v_cvt_pk_bf16_f32 v241, v26, v27
	global_store_dwordx2 v223, v[240:241], s[8:9] offset:64
	v_cvt_pk_bf16_f32 v240, v28, v29
	v_cvt_pk_bf16_f32 v241, v30, v31
	global_store_dwordx2 v223, v[240:241], s[8:9] offset:96
	v_add_u32_e32 v223, s3, v87
	v_lshlrev_b32_e32 v223, 10, v223
	s_lshl_b32 s2, s36, 7
	v_add_u32_e32 v223, s2, v223
	v_lshl_add_u32 v223, v113, 3, v223
	v_cvt_pk_bf16_f32 v240, v32, v33
	v_cvt_pk_bf16_f32 v241, v34, v35
	global_store_dwordx2 v223, v[240:241], s[8:9] offset:0
	v_cvt_pk_bf16_f32 v240, v36, v37
	v_cvt_pk_bf16_f32 v241, v38, v39
	global_store_dwordx2 v223, v[240:241], s[8:9] offset:32
	v_cvt_pk_bf16_f32 v240, v40, v41
	v_cvt_pk_bf16_f32 v241, v42, v43
	global_store_dwordx2 v223, v[240:241], s[8:9] offset:64
	v_cvt_pk_bf16_f32 v240, v44, v45
	v_cvt_pk_bf16_f32 v241, v46, v47
	global_store_dwordx2 v223, v[240:241], s[8:9] offset:96
	s_add_i32 s26, s26, s92
	s_cmpk_lt_i32 s26, 0x400
	s_cbranch_scc1 .Lnsa_task
